# v14 plus attention tile stores issued early in the PV block with precise vmcnt waits
# speedup vs baseline: 1.0169x; 1.0053x over previous
; #define LAS __attribute__((address_space(3)))
; __device__ __forceinline__ void attn_unit(const Ctx& C, int qrow0, int krow0, int h, int NT, int ntw) {
;     const bf16_t* Q = (const bf16_t*)(C.ws + WS_ZRX); const bf16_t* KN = (const bf16_t*)(C.ws + WS_ZRG); const bf16_t* KRp = (const bf16_t*)(C.ws + WS_KR);
;     const bf16_t* VT = (const bf16_t*)(C.ws + WS_AB); bf16_t* O = (bf16_t*)(C.ws + WS_ZA);
;     int tid_ = threadIdx.x; asm volatile("" : "+v"(tid_));
;     const int tid = tid_, lane = tid & 63, wid = __builtin_amdgcn_readfirstlane(tid >> 6), r32 = lane & 31, hi = lane >> 5;
;     LAS unsigned char* lds = C.lds;
;     bf16x8 qr[6];
;     if (ntw > 0) {
; #pragma unroll
;         for (int ds = 0; ds < 6; ++ds) qr[ds] = *(const bf16x8*)(Q + (size_t)(qrow0 + wid * 32 + r32) * 768 + h * 96 + ds * 16 + hi * 8);
;     } else {
; #pragma unroll
;         for (int ds = 0; ds < 6; ++ds) qr[ds] = (bf16x8){0, 0, 0, 0, 0, 0, 0, 0};
;     }
;     const bf16_t* ksrc = KN + (size_t)(krow0 + (tid >> 3)) * 512 + h * 64 + (tid & 7) * 8;
;     const bf16_t* rsrc = KRp + (size_t)(krow0 + ((tid & 255) >> 2)) * 32 + (tid & 3) * 8;
;     const bf16_t* vsrc = VT + (size_t)(h * 64 + (tid >> 3)) * KVROWS + krow0 + (tid & 7) * 8;
;     const int kdst = (tid >> 3) * KT_STRIDE + (tid & 7) * 16, rdst = ((tid & 255) >> 2) * KT_STRIDE + 128 + (tid & 3) * 16;
;     const int vdst = AT_V0 + (tid >> 3) * VT_STRIDE + (((tid & 7) >> 1) * 16 + 4 * (tid & 1)) * 2;
;     u32x4 kA, rA, vA, kB, rB, vB;
;     ...
;     f32x16 o0 = {}, o1 = {}, negm = {}; float mrun = 0.f, lrun = 0.f;
;     asm volatile("" : "+v"(negm));
;     if (wid >= 4) __builtin_amdgcn_s_setprio(1);
.LBB0_1162:
	s_and_b64 s[0:1], s[60:61], exec
	s_cselect_b32 s47, s73, s72
	s_lshl_b32 s0, s47, 8
	v_mov_b32_e32 v32, v1
	s_or_b32 s0, s0, s46
	v_mov_b64_e32 v[4:5], s[50:51]
	v_readfirstlane_b32 s1, v32
	v_and_b32_e32 v38, 31, v32
	s_ashr_i32 s6, s1, 6
	s_lshr_b32 s98, s6, 2
	v_or_b32_e32 v2, s0, v38
	v_bfe_u32 v152, v32, 5, 1
	v_lshl_add_u32 v142, s6, 5, v2
	v_mad_i64_i32 v[4:5], s[0:1], v142, s41, v[4:5]
	v_lshlrev_b32_e32 v2, 4, v152
	v_lshl_add_u64 v[4:5], v[4:5], 0, v[2:3]
	global_load_dwordx4 v[104:107], v[4:5], off
	global_load_dwordx4 v[100:103], v[4:5], off offset:32
	global_load_dwordx4 v[96:99], v[4:5], off offset:64
	global_load_dwordx4 v[92:95], v[4:5], off offset:96
	global_load_dwordx4 v[88:91], v[4:5], off offset:128
	global_load_dwordx4 v[84:87], v[4:5], off offset:160
	v_mov_b32_e32 v4, v3
	v_mov_b32_e32 v5, v3
	v_mov_b32_e32 v6, v3
	v_mov_b32_e32 v7, v3
	v_mov_b32_e32 v8, v3
	v_mov_b32_e32 v9, v3
	v_mov_b32_e32 v10, v3
	v_mov_b32_e32 v11, v3
	v_mov_b32_e32 v12, v3
	v_mov_b32_e32 v13, v3
	v_mov_b32_e32 v14, v3
	v_mov_b32_e32 v15, v3
	v_mov_b32_e32 v16, v3
	v_mov_b32_e32 v17, v3
	v_mov_b32_e32 v18, v3
	v_mov_b32_e32 v19, v3
	s_cmp_lt_i32 s6, 4
	s_cbranch_scc1 .LBB0_1164
	s_setprio 1

; #define AT_LOAD(t, K_, R_, V_) do { K_ = *(const u32x4*)(ksrc + (size_t)(t) * 64 * 512); if (tid < 256) R_ = *(const u32x4*)(rsrc + (size_t)(t) * 64 * 32); V_ = *(const u32x4*)(vsrc + (size_t)(t) * 64); } while (0)
; #define AT_STORE(t, K_, R_, V_) do { LAS unsigned char* sk = lds + AT_K0 + ((t) & 1) * KT_BYTES; *(LAS u32x4*)(sk + kdst) = K_; if (tid < 256) *(LAS u32x4*)(sk + rdst) = R_; \
;         LAS unsigned char* sv = lds + ((t) & 1) * VT_BYTES; *(LAS u32x2*)(sv + vdst) = (u32x2){V_.x, V_.y}; *(LAS u32x2*)(sv + vdst + 16) = (u32x2){V_.z, V_.w}; } while (0)
; #define AT_BAR() asm volatile("s_waitcnt lgkmcnt(0)\n\ts_barrier" ::: "memory")
; __device__ __forceinline__ void attn_unit(const Ctx& C, int qrow0, int krow0, int h, int NT, int ntw) {
;     ...
;     for (; t + 1 < NT; t += 2) {
;         if (t + 2 < NT) AT_LOAD(t + 2, kB, rB, vB);
;         if (t < ntw) at_step<false>(o0, o1, negm, mrun, lrun, qr, Kl + KT_BYTES, Vl + VT_BYTES);
;         AT_STORE(t + 1, kA, rA, vA);
;         AT_BAR();
;         if (t + 3 < NT) AT_LOAD(t + 3, kA, rA, vA);
;         if (t + 1 < ntw) at_step<false>(o0, o1, negm, mrun, lrun, qr, Kl, Vl);
.Lat_e1:
	s_add_i32 s75, s16, 2
	s_waitcnt lgkmcnt(0)
	s_barrier
	s_cmp_ge_u32 s75, s74
	s_cselect_b64 s[62:63], -1, 0
	s_and_b64 vcc, exec, s[62:63]
	s_cbranch_vccz .LBB0_1191
	s_cmp_gt_u32 s16, s47
	s_cbranch_scc0 .LBB0_1194

; #define LAS __attribute__((address_space(3)))
; #define AT_GA(g) { bf16x8 na = ka; if ((g) < 5) na = *(const LAS bf16x8*)(Kb + ((g) + 1) * 32); else na = *(const LAS bf16x8*)(Kb + 32 * KT_STRIDE); \
;         if ((g) == 0) C0 = AT_MFMA(ka, qr[0], negm, 0, 0, 0); else C0 = AT_MFMA(ka, qr[g], C0, 0, 0, 0); ka = na; }
; #define AT_GA(g) { bf16x8 na = ka; if ((g) < 5) na = *(const LAS bf16x8*)(Kb + 32 * KT_STRIDE + ((g) + 1) * 32); \
;         if ((g) == 0) C1 = AT_MFMA(ka, qr[0], negm, 0, 0, 0); else C1 = AT_MFMA(ka, qr[g], C1, 0, 0, 0); ka = na; }
; template <bool FIRST>
; __device__ __forceinline__ void at_step(f32x16& o0, f32x16& o1, f32x16& negm, float& mrun, float& lrun, const bf16x8 (&qr)[6], const LAS unsigned char* Kb, const LAS unsigned char* Vb) {
;     ...
;     {   bf16x8 ka = *(const LAS bf16x8*)(Kb);
;     ...
;         AT_GA(0) AT_GA(1) AT_GA(2) AT_GA(3) AT_GA(4) AT_GA(5)
;     ...
;         AT_GA(0) AT_GA(1) AT_GA(2) AT_GA(3) AT_GA(4) AT_GA(5)
;     ...
;     }
;     bf16x8 va = *(const LAS bf16x8*)(Vb), vb = *(const LAS bf16x8*)(Vb + 32 * VT_STRIDE);
;     float sacc = 0.f;
;     ...
;     {   float rm = fmaxf(fmaxf(C0[0], C0[1]), C0[2]);
; #pragma unroll
;         for (int r = 3; r < 15; r += 2) rm = fmaxf(fmaxf(rm, C0[r]), C0[r + 1]);
;         rm = fmaxf(rm, C0[15]);
;         rm = fmaxf(rm, __shfl_xor(rm, 32));
;         if (FIRST) { const float dl = rm; mrun = dl;
; #pragma unroll
;             for (int r = 0; r < 16; ++r) { C0[r] -= dl; C1[r] -= dl; negm[r] = -mrun; }
;             asm volatile("" : "+v"(negm));
;         } else if (__builtin_expect(__any(rm > 8.f), 0)) { const float dl = fmaxf(rm, 0.f); mrun += dl;
.Lat1_c3:
	s_waitcnt lgkmcnt(9)
	v_mfma_f32_32x32x16_bf16 v[68:83], v[186:189], v[96:99], v[68:83]
	s_waitcnt lgkmcnt(8)
	v_mfma_f32_32x32x16_bf16 v[68:83], v[190:193], v[92:95], v[68:83]
	s_waitcnt lgkmcnt(7)
	v_mfma_f32_32x32x16_bf16 v[68:83], v[194:197], v[88:91], v[68:83]
	s_waitcnt lgkmcnt(6)
	v_mfma_f32_32x32x16_bf16 v[68:83], v[198:201], v[84:87], v[68:83]
	ds_read_b128 v[136:139], v154 offset:35840
	ds_read_b128 v[132:135], v154 offset:40448
	s_waitcnt lgkmcnt(7)
	v_mfma_f32_32x32x16_bf16 v[52:67], v[202:205], v[104:107], v[36:51]
	s_waitcnt lgkmcnt(6)
	v_mfma_f32_32x32x16_bf16 v[52:67], v[206:209], v[100:103], v[52:67]
	s_waitcnt lgkmcnt(5)
	v_mfma_f32_32x32x16_bf16 v[52:67], v[210:213], v[96:99], v[52:67]
	s_waitcnt lgkmcnt(4)
	v_mfma_f32_32x32x16_bf16 v[52:67], v[214:217], v[92:95], v[52:67]
	s_nop 1
	v_max3_f32 v226, v68, v69, v70
	v_max3_f32 v226, v226, v71, v72
	v_max3_f32 v226, v226, v73, v74
	v_max3_f32 v226, v226, v75, v76
	v_max3_f32 v226, v226, v77, v78
	v_max3_f32 v226, v226, v79, v80
	v_max3_f32 v226, v226, v81, v82
	v_max_f32_e32 v158, v226, v83
	v_mov_b32_e32 v159, v158
	s_waitcnt lgkmcnt(3)
	v_mfma_f32_32x32x16_bf16 v[52:67], v[218:221], v[88:91], v[52:67]
	v_permlane32_swap_b32_e32 v158, v159
	s_waitcnt lgkmcnt(2)
	v_mfma_f32_32x32x16_bf16 v[52:67], v[222:225], v[84:87], v[52:67]
	v_max_f32_e32 v163, v158, v159
	v_cmp_lt_f32_e32 vcc, s70, v163
	s_cbranch_vccnz .LBB0_1202

; #define AT_LOAD(t, K_, R_, V_) do { K_ = *(const u32x4*)(ksrc + (size_t)(t) * 64 * 512); if (tid < 256) R_ = *(const u32x4*)(rsrc + (size_t)(t) * 64 * 32); V_ = *(const u32x4*)(vsrc + (size_t)(t) * 64); } while (0)
; #define AT_STORE(t, K_, R_, V_) do { LAS unsigned char* sk = lds + AT_K0 + ((t) & 1) * KT_BYTES; *(LAS u32x4*)(sk + kdst) = K_; if (tid < 256) *(LAS u32x4*)(sk + rdst) = R_; \
;         LAS unsigned char* sv = lds + ((t) & 1) * VT_BYTES; *(LAS u32x2*)(sv + vdst) = (u32x2){V_.x, V_.y}; *(LAS u32x2*)(sv + vdst + 16) = (u32x2){V_.z, V_.w}; } while (0)
; __device__ __forceinline__ void attn_unit(const Ctx& C, int qrow0, int krow0, int h, int NT, int ntw) {
;     ...
;         if (t + 2 < NT) AT_LOAD(t + 2, kB, rB, vB);
;         if (t < ntw) at_step<false>(o0, o1, negm, mrun, lrun, qr, Kl + KT_BYTES, Vl + VT_BYTES);
;         AT_STORE(t + 1, kA, rA, vA);
.LBB0_1190:
	s_cmp_lg_u64 s[60:61], 0
	s_cbranch_scc1 .Lst1_a
	s_waitcnt vmcnt(0)
	s_branch .Lst1_b
.Lst1_a:
	s_waitcnt vmcnt(3)
.Lst1_b:
	ds_write_b128 v155, v[124:127]
	s_cmp_lg_u32 s98, 0
	s_cbranch_scc1 .Lst1_hi
	ds_write_b128 v160, v[108:111] offset:128
	s_branch .Lst1_v

; template <bool FIRST>
; __device__ __forceinline__ void at_step(f32x16& o0, f32x16& o1, f32x16& negm, float& mrun, float& lrun, const bf16x8 (&qr)[6], const LAS unsigned char* Kb, const LAS unsigned char* Vb) {
;     ...
;     AT_GB(2, C1, 0) AT_GB(3, C1, 8)
;     ...
;     lrun += sacc;
.Lst1_v:
	ds_write2_b64 v157, v[128:129], v[130:131] offset1:2
	v_exp_f32_e32 v79, v52
	v_exp_f32_e32 v81, v53
	v_exp_f32_e32 v83, v54
	v_exp_f32_e32 v133, v55
	v_exp_f32_e32 v135, v56
	v_exp_f32_e32 v137, v57
	v_exp_f32_e32 v139, v58
	v_exp_f32_e32 v159, v59
	v_cvt_pk_bf16_f32 v52, v79, v81
	v_cvt_pk_bf16_f32 v53, v83, v133
	v_cvt_pk_bf16_f32 v54, v135, v137
	v_cvt_pk_bf16_f32 v55, v139, v159
	v_exp_f32_e32 v134, v60
	v_exp_f32_e32 v136, v61
	v_mfma_f32_32x32x16_bf16 v[20:35], v[72:75], v[52:55], v[20:35]
	ds_read_b128 v[56:59], v154 offset:35936
	ds_read_b128 v[72:75], v154 offset:40544
	v_exp_f32_e32 v138, v62
	v_exp_f32_e32 v158, v63
	v_exp_f32_e32 v82, v64
	v_exp_f32_e32 v132, v65
	v_exp_f32_e32 v80, v66
	v_exp_f32_e32 v78, v67
	v_mfma_f32_32x32x16_bf16 v[4:19], v[68:71], v[52:55], v[4:19]
	v_cvt_pk_bf16_f32 v52, v134, v136
	v_cvt_pk_bf16_f32 v53, v138, v158
	v_cvt_pk_bf16_f32 v54, v82, v132
	v_cvt_pk_bf16_f32 v55, v80, v78
	v_add_f32_e64 v60, v136, v134
	v_add_f32_e64 v61, v137, v135
	v_pk_add_f32 v[62:63], v[158:159], v[138:139]
	s_waitcnt lgkmcnt(1)
	v_mfma_f32_32x32x16_bf16 v[20:35], v[56:59], v[52:55], v[20:35]
	v_add_f32_e64 v56, v62, v60
	v_add_f32_e64 v57, v63, v61
	v_add_f32_e64 v58, v132, v82
	v_add_f32_e64 v59, v133, v83
	v_add_f32_e64 v60, v80, v78
	v_add_f32_e64 v61, v81, v79
	v_pk_add_f32 v[58:59], v[58:59], v[60:61]
	s_nop 0
	v_pk_add_f32 v[56:57], v[56:57], v[58:59]
	s_waitcnt lgkmcnt(0)
	v_mfma_f32_32x32x16_bf16 v[4:19], v[72:75], v[52:55], v[4:19]
	v_add_f32_e32 v57, 0, v57
	v_add_f32_e32 v56, v56, v57
	v_add_f32_e32 v162, v76, v56
	s_branch .Lat_e1

; #define LAS __attribute__((address_space(3)))
; #define AT_GA(g) { bf16x8 na = ka; if ((g) < 5) na = *(const LAS bf16x8*)(Kb + ((g) + 1) * 32); else na = *(const LAS bf16x8*)(Kb + 32 * KT_STRIDE); \
;         if ((g) == 0) C0 = AT_MFMA(ka, qr[0], negm, 0, 0, 0); else C0 = AT_MFMA(ka, qr[g], C0, 0, 0, 0); ka = na; }
; #define AT_GA(g) { bf16x8 na = ka; if ((g) < 5) na = *(const LAS bf16x8*)(Kb + 32 * KT_STRIDE + ((g) + 1) * 32); \
;         if ((g) == 0) C1 = AT_MFMA(ka, qr[0], negm, 0, 0, 0); else C1 = AT_MFMA(ka, qr[g], C1, 0, 0, 0); ka = na; }
; template <bool FIRST>
; __device__ __forceinline__ void at_step(f32x16& o0, f32x16& o1, f32x16& negm, float& mrun, float& lrun, const bf16x8 (&qr)[6], const LAS unsigned char* Kb, const LAS unsigned char* Vb) {
;     ...
;     {   bf16x8 ka = *(const LAS bf16x8*)(Kb);
;     ...
;         AT_GA(0) AT_GA(1) AT_GA(2) AT_GA(3) AT_GA(4) AT_GA(5)
;     ...
;         AT_GA(0) AT_GA(1) AT_GA(2) AT_GA(3) AT_GA(4) AT_GA(5)
;     ...
;     }
;     bf16x8 va = *(const LAS bf16x8*)(Vb), vb = *(const LAS bf16x8*)(Vb + 32 * VT_STRIDE);
;     float sacc = 0.f;
;     ...
;     {   float rm = fmaxf(fmaxf(C0[0], C0[1]), C0[2]);
; #pragma unroll
;         for (int r = 3; r < 15; r += 2) rm = fmaxf(fmaxf(rm, C0[r]), C0[r + 1]);
;         rm = fmaxf(rm, C0[15]);
;         rm = fmaxf(rm, __shfl_xor(rm, 32));
;         if (FIRST) { const float dl = rm; mrun = dl;
; #pragma unroll
;             for (int r = 0; r < 16; ++r) { C0[r] -= dl; C1[r] -= dl; negm[r] = -mrun; }
;             asm volatile("" : "+v"(negm));
;         } else if (__builtin_expect(__any(rm > 8.f), 0)) { const float dl = fmaxf(rm, 0.f); mrun += dl;
.Lat2_c3:
	s_waitcnt lgkmcnt(9)
	v_mfma_f32_32x32x16_bf16 v[68:83], v[186:189], v[96:99], v[68:83]
	s_waitcnt lgkmcnt(8)
	v_mfma_f32_32x32x16_bf16 v[68:83], v[190:193], v[92:95], v[68:83]
	s_waitcnt lgkmcnt(7)
	v_mfma_f32_32x32x16_bf16 v[68:83], v[194:197], v[88:91], v[68:83]
	s_waitcnt lgkmcnt(6)
	v_mfma_f32_32x32x16_bf16 v[68:83], v[198:201], v[84:87], v[68:83]
	ds_read_b128 v[136:139], v154 offset:26624
	ds_read_b128 v[132:135], v154 offset:31232
	s_waitcnt lgkmcnt(7)
	v_mfma_f32_32x32x16_bf16 v[52:67], v[202:205], v[104:107], v[36:51]
	s_waitcnt lgkmcnt(6)
	v_mfma_f32_32x32x16_bf16 v[52:67], v[206:209], v[100:103], v[52:67]
	s_waitcnt lgkmcnt(5)
	v_mfma_f32_32x32x16_bf16 v[52:67], v[210:213], v[96:99], v[52:67]
	s_waitcnt lgkmcnt(4)
	v_mfma_f32_32x32x16_bf16 v[52:67], v[214:217], v[92:95], v[52:67]
	s_nop 1
	v_max3_f32 v226, v68, v69, v70
	v_max3_f32 v226, v226, v71, v72
	v_max3_f32 v226, v226, v73, v74
	v_max3_f32 v226, v226, v75, v76
	v_max3_f32 v226, v226, v77, v78
	v_max3_f32 v226, v226, v79, v80
	v_max3_f32 v226, v226, v81, v82
	v_max_f32_e32 v150, v226, v83
	v_mov_b32_e32 v151, v150
	s_waitcnt lgkmcnt(3)
	v_mfma_f32_32x32x16_bf16 v[52:67], v[218:221], v[88:91], v[52:67]
	v_permlane32_swap_b32_e32 v150, v151
	s_waitcnt lgkmcnt(2)
	v_mfma_f32_32x32x16_bf16 v[52:67], v[222:225], v[84:87], v[52:67]
	v_max_f32_e32 v150, v150, v151
	v_cmp_lt_f32_e32 vcc, s70, v150
	s_cbranch_vccnz .LBB0_1204

; #define AT_STORE(t, K_, R_, V_) do { LAS unsigned char* sk = lds + AT_K0 + ((t) & 1) * KT_BYTES; *(LAS u32x4*)(sk + kdst) = K_; if (tid < 256) *(LAS u32x4*)(sk + rdst) = R_; \
;         LAS unsigned char* sv = lds + ((t) & 1) * VT_BYTES; *(LAS u32x2*)(sv + vdst) = (u32x2){V_.x, V_.y}; *(LAS u32x2*)(sv + vdst + 16) = (u32x2){V_.z, V_.w}; } while (0)
; __device__ __forceinline__ void attn_unit(const Ctx& C, int qrow0, int krow0, int h, int NT, int ntw) {
;     ...
;         if (t + 2 < NT) AT_STORE(t + 2, kB, rB, vB);
.LBB0_1196:
	s_cmp_lg_u64 s[60:61], 0
	s_cbranch_scc0 .Lst2_none
	s_cmp_lg_u64 s[62:63], 0
	s_cbranch_scc0 .Lst2_a
	s_waitcnt vmcnt(0)
	s_branch .Lst2_b

; #define AT_STORE(t, K_, R_, V_) do { LAS unsigned char* sk = lds + AT_K0 + ((t) & 1) * KT_BYTES; *(LAS u32x4*)(sk + kdst) = K_; if (tid < 256) *(LAS u32x4*)(sk + rdst) = R_; \
;         LAS unsigned char* sv = lds + ((t) & 1) * VT_BYTES; *(LAS u32x2*)(sv + vdst) = (u32x2){V_.x, V_.y}; *(LAS u32x2*)(sv + vdst + 16) = (u32x2){V_.z, V_.w}; } while (0)
; __device__ __forceinline__ void attn_unit(const Ctx& C, int qrow0, int krow0, int h, int NT, int ntw) {
;     ...
;         if (t + 2 < NT) AT_STORE(t + 2, kB, rB, vB);
.Lst2_b:
	ds_write_b128 v155, v[112:115] offset:13312
	s_cmp_lg_u32 s98, 0
	s_cbranch_scc1 .Lst2_hi
	ds_write_b128 v160, v[116:119] offset:13440
	s_branch .Lst2_v

; #define AT_STORE(t, K_, R_, V_) do { LAS unsigned char* sk = lds + AT_K0 + ((t) & 1) * KT_BYTES; *(LAS u32x4*)(sk + kdst) = K_; if (tid < 256) *(LAS u32x4*)(sk + rdst) = R_; \
;         LAS unsigned char* sv = lds + ((t) & 1) * VT_BYTES; *(LAS u32x2*)(sv + vdst) = (u32x2){V_.x, V_.y}; *(LAS u32x2*)(sv + vdst + 16) = (u32x2){V_.z, V_.w}; } while (0)
; #define AT_BAR() asm volatile("s_waitcnt lgkmcnt(0)\n\ts_barrier" ::: "memory")
; template <bool FIRST>
; __device__ __forceinline__ void at_step(f32x16& o0, f32x16& o1, f32x16& negm, float& mrun, float& lrun, const bf16x8 (&qr)[6], const LAS unsigned char* Kb, const LAS unsigned char* Vb) {
;     ...
;     AT_GB(2, C1, 0) AT_GB(3, C1, 8)
;     ...
;     lrun += sacc;
; __device__ __forceinline__ void attn_unit(const Ctx& C, int qrow0, int krow0, int h, int NT, int ntw) {
;     ...
;         if (t + 2 < NT) AT_STORE(t + 2, kB, rB, vB);
;         AT_BAR();
.Lst2_v:
	ds_write2_b64 v161, v[120:121], v[122:123] offset0:128 offset1:130
.Lst2_none:
	v_exp_f32_e32 v79, v52
	v_exp_f32_e32 v81, v53
	v_exp_f32_e32 v83, v54
	v_exp_f32_e32 v133, v55
	v_exp_f32_e32 v135, v56
	v_exp_f32_e32 v137, v57
	v_exp_f32_e32 v139, v58
	v_exp_f32_e32 v151, v59
	v_cvt_pk_bf16_f32 v52, v79, v81
	v_cvt_pk_bf16_f32 v53, v83, v133
	v_cvt_pk_bf16_f32 v54, v135, v137
	v_cvt_pk_bf16_f32 v55, v139, v151
	v_exp_f32_e32 v134, v60
	v_exp_f32_e32 v136, v61
	v_mfma_f32_32x32x16_bf16 v[20:35], v[72:75], v[52:55], v[20:35]
	ds_read_b128 v[56:59], v154 offset:26720
	ds_read_b128 v[72:75], v154 offset:31328
	v_exp_f32_e32 v138, v62
	v_exp_f32_e32 v150, v63
	v_exp_f32_e32 v82, v64
	v_exp_f32_e32 v132, v65
	v_exp_f32_e32 v80, v66
	v_exp_f32_e32 v78, v67
	v_mfma_f32_32x32x16_bf16 v[4:19], v[68:71], v[52:55], v[4:19]
	v_cvt_pk_bf16_f32 v52, v134, v136
	v_cvt_pk_bf16_f32 v53, v138, v150
	v_cvt_pk_bf16_f32 v54, v82, v132
	v_cvt_pk_bf16_f32 v55, v80, v78
	v_add_f32_e64 v60, v136, v134
	v_add_f32_e64 v61, v137, v135
	v_pk_add_f32 v[62:63], v[150:151], v[138:139]
	s_waitcnt lgkmcnt(1)
	v_mfma_f32_32x32x16_bf16 v[20:35], v[56:59], v[52:55], v[20:35]
	v_add_f32_e64 v56, v62, v60
	v_add_f32_e64 v57, v63, v61
	v_add_f32_e64 v58, v132, v82
	v_add_f32_e64 v59, v133, v83
	v_add_f32_e64 v60, v80, v78
	v_add_f32_e64 v61, v81, v79
	v_pk_add_f32 v[58:59], v[58:59], v[60:61]
	s_nop 0
	v_pk_add_f32 v[56:57], v[56:57], v[58:59]
	s_waitcnt lgkmcnt(0)
	v_mfma_f32_32x32x16_bf16 v[4:19], v[72:75], v[52:55], v[4:19]
	v_add_f32_e32 v57, 0, v57
	v_add_f32_e32 v56, v56, v57
	v_add_f32_e32 v162, v76, v56
	v_cndmask_b32_e64 v52, 0, 1, s[60:61]
	v_cmp_ne_u32_e64 s[0:1], 1, v52
	s_branch .LBB0_1200

; __global__ void __launch_bounds__(512, 2) mk_fwd(Args args) {
;     run_phases(args, 0, NPHASE);
;     if (args.ph_hi > NPHASE + 100) cg::this_grid().sync();
; }
	.amdhsa_kernel _Z6mk_fwd4Args
		.amdhsa_group_segment_fixed_size 0
		.amdhsa_private_segment_fixed_size 0
		.amdhsa_kernarg_size 528
		.amdhsa_user_sgpr_count 2
		.amdhsa_user_sgpr_dispatch_ptr 0
		.amdhsa_user_sgpr_queue_ptr 0
		.amdhsa_user_sgpr_kernarg_segment_ptr 1
		.amdhsa_user_sgpr_dispatch_id 0
		.amdhsa_user_sgpr_kernarg_preload_length 0
		.amdhsa_user_sgpr_kernarg_preload_offset 0
		.amdhsa_user_sgpr_private_segment_size 0
		.amdhsa_uses_dynamic_stack 0
		.amdhsa_enable_private_segment 0
		.amdhsa_system_sgpr_workgroup_id_x 1
		.amdhsa_system_sgpr_workgroup_id_y 0
		.amdhsa_system_sgpr_workgroup_id_z 0
		.amdhsa_system_sgpr_workgroup_info 0
		.amdhsa_system_vgpr_workitem_id 2
		.amdhsa_next_free_vgpr 256
		.amdhsa_next_free_sgpr 102
		.amdhsa_accum_offset 256
		.amdhsa_reserve_vcc 1
		.amdhsa_float_round_mode_32 0
		.amdhsa_float_round_mode_16_64 0
		.amdhsa_float_denorm_mode_32 3
		.amdhsa_float_denorm_mode_16_64 3
		.amdhsa_dx10_clamp 1
		.amdhsa_ieee_mode 1
		.amdhsa_fp16_overflow 0
		.amdhsa_tg_split 0
		.amdhsa_exception_fp_ieee_invalid_op 0
		.amdhsa_exception_fp_denorm_src 0
		.amdhsa_exception_fp_ieee_div_zero 0
		.amdhsa_exception_fp_ieee_overflow 0
		.amdhsa_exception_fp_ieee_underflow 0
		.amdhsa_exception_fp_ieee_inexact 0
		.amdhsa_exception_int_div_zero 0
	.end_amdhsa_kernel

; __global__ void __launch_bounds__(512, 2) mk_fwd(Args args) {
;     run_phases(args, 0, NPHASE);
;     if (args.ph_hi > NPHASE + 100) cg::this_grid().sync();
; }
amdhsa.kernels:
  - .agpr_count:     0
    .args:
      - .offset:         0
        .size:           272
        .value_kind:     by_value
      - .offset:         272
        .size:           4
        .value_kind:     hidden_block_count_x
      - .offset:         276
        .size:           4
        .value_kind:     hidden_block_count_y
      - .offset:         280
        .size:           4
        .value_kind:     hidden_block_count_z
      - .offset:         284
        .size:           2
        .value_kind:     hidden_group_size_x
      - .offset:         286
        .size:           2
        .value_kind:     hidden_group_size_y
      - .offset:         288
        .size:           2
        .value_kind:     hidden_group_size_z
      - .offset:         290
        .size:           2
        .value_kind:     hidden_remainder_x
      - .offset:         292
        .size:           2
        .value_kind:     hidden_remainder_y
      - .offset:         294
        .size:           2
        .value_kind:     hidden_remainder_z
      - .offset:         312
        .size:           8
        .value_kind:     hidden_global_offset_x
      - .offset:         320
        .size:           8
        .value_kind:     hidden_global_offset_y
      - .offset:         328
        .size:           8
        .value_kind:     hidden_global_offset_z
      - .offset:         336
        .size:           2
        .value_kind:     hidden_grid_dims
      - .offset:         360
        .size:           8
        .value_kind:     hidden_multigrid_sync_arg
      - .offset:         392
        .size:           4
        .value_kind:     hidden_dynamic_lds_size
    .group_segment_fixed_size: 0
    .kernarg_segment_align: 8
    .kernarg_segment_size: 528
    .language:       OpenCL C
    .language_version:
      - 2
      - 0
    .max_flat_workgroup_size: 512
    .name:           _Z6mk_fwd4Args
    .private_segment_fixed_size: 0
    .sgpr_count:     108
    .sgpr_spill_count: 47
    .symbol:         _Z6mk_fwd4Args.kd
    .uniform_work_group_size: 1
    .uses_dynamic_stack: false
    .vgpr_count:     256
    .vgpr_spill_count: 0
    .wavefront_size: 64
